# micro1 plus prologue fence: every wave drains its stores, barrier, then only wave 0 issues buffer_wbl2/buffer_inv (1 instead of 8 write-back commands per workgroup) before the cooperative grid sync
# speedup vs baseline: 1.0325x; 1.0325x over previous
; __global__ void __launch_bounds__(NTHREADS, 2) fwd_megakernel(Params P) {
;     ...
;     __threadfence();
;     __syncthreads();
;     grid.sync();
.LBB0_84:
	s_or_b64 exec, exec, s[16:17]
	v_lshrrev_b32_e32 v1, 20, v0
	v_lshrrev_b32_e32 v0, 10, v0
	v_or_b32_e32 v0, v0, v1
	s_movk_i32 s0, 0x3ff
	v_and_or_b32 v0, v0, s0, v202
	v_cmp_eq_u32_e32 vcc, 0, v0
	v_readfirstlane_b32 s100, v202
	s_waitcnt vmcnt(0) lgkmcnt(0)
	s_barrier
	s_lshr_b32 s100, s100, 6
	s_cmp_eq_u32 s100, 0
	s_cbranch_scc0 .Lpro_nofence
	buffer_wbl2 sc1
	s_waitcnt vmcnt(0)
	buffer_inv sc1
.Lpro_nofence:
	s_barrier
	s_and_saveexec_b64 s[0:1], vcc
	v_readlane_b32 s16, v250, 0
	v_readlane_b32 s18, v250, 2
	v_readlane_b32 s19, v250, 3
	v_readlane_b32 s17, v250, 1
	s_cbranch_execz .LBB0_94
	buffer_wbl2 sc1
	s_load_dwordx2 s[4:5], s[34:35], 0x58
	v_mov_b32_e32 v2, 0
	s_mov_b64 s[6:7], exec
	v_mbcnt_lo_u32_b32 v1, s6, 0
	v_mbcnt_hi_u32_b32 v1, s7, v1
	s_waitcnt lgkmcnt(0)
	global_load_dword v0, v2, s[4:5] offset:40
	v_cmp_eq_u32_e32 vcc, 0, v1
	s_and_saveexec_b64 s[8:9], vcc
	s_cbranch_execz .LBB0_87
	s_bcnt1_i32_b64 s6, s[6:7]
	v_mov_b32_e32 v3, s6
	global_atomic_add v3, v2, v3, s[4:5] offset:32 sc0
